# adds: P2 EpiKV all ssqp loads up front (counted vmcnt); P9 conv loop v2 processes two consecutive rows per iteration (each staged row unpacked once, t-mask only on rare path)
# speedup vs baseline: 1.0469x; 1.0126x over previous
.LBB0_456:
	s_lshl_b32 s0, s78, 8
	s_add_i32 s0, s0, s67
	v_and_b32_e32 v136, 48, v191
	v_and_or_b32 v151, v191, 15, s0
	v_lshlrev_b32_e32 v184, 4, v151
	v_add_u32_e32 v187, 0x200000, v184
	v_add_u32_e32 v184, 0x180000, v184
	v_lshl_add_u32 v185, v151, 11, v136
	s_lshl_b32 s0, s79, 9
	s_add_u32 s0, s40, s0
	s_addc_u32 s1, s41, 0
	s_add_u32 s0, s0, s6
	s_addc_u32 s1, s1, s7
	global_load_dwordx4 v[152:155], v184, s[8:9]
	global_load_dwordx4 v[192:195], v187, s[8:9]
	global_load_dwordx4 v[156:159], v184, s[8:9] offset:256
	global_load_dwordx4 v[196:199], v187, s[8:9] offset:256
	global_load_dwordx4 v[160:163], v184, s[8:9] offset:512
	global_load_dwordx4 v[200:203], v187, s[8:9] offset:512
	global_load_dwordx4 v[164:167], v184, s[8:9] offset:768
	global_load_dwordx4 v[204:207], v187, s[8:9] offset:768
	global_load_dwordx4 v[168:171], v184, s[8:9] offset:2048
	global_load_dwordx4 v[208:211], v187, s[8:9] offset:2048
	global_load_dwordx4 v[172:175], v184, s[8:9] offset:2304
	global_load_dwordx4 v[212:215], v187, s[8:9] offset:2304
	global_load_dwordx4 v[176:179], v184, s[8:9] offset:2560
	global_load_dwordx4 v[216:219], v187, s[8:9] offset:2560
	global_load_dwordx4 v[180:183], v184, s[8:9] offset:2816
	global_load_dwordx4 v[220:223], v187, s[8:9] offset:2816
	s_waitcnt vmcnt(14)
	v_pk_add_f32 v[188:189], v[152:153], v[154:155]
	v_pk_add_f32 v[224:225], v[192:193], v[194:195]
	v_mov_b32_e32 v186, v185
	v_pk_add_f32 v[188:189], v[188:189], v[224:225]
	s_nop 0
	v_add_f32_e32 v188, v188, v189
	v_fmamk_f32 v188, v188, 0x3b800000, v150
	v_mul_f32_e32 v189, 0x4b800000, v188
	v_cmp_gt_f32_e32 vcc, s75, v188
	s_nop 1
	v_cndmask_b32_e32 v188, v188, v189, vcc
	v_rsq_f32_e32 v226, v188
	s_nop 0
	v_mul_f32_e32 v227, 0x45800000, v226
	v_cndmask_b32_e32 v226, v226, v227, vcc
	v_pk_mul_f32 v[124:125], v[124:125], v[226:227] op_sel_hi:[1,0]
	v_pk_mul_f32 v[126:127], v[126:127], v[226:227] op_sel_hi:[1,0]
	v_pk_mul_f32 v[120:121], v[120:121], v[226:227] op_sel_hi:[1,0]
	v_pk_mul_f32 v[122:123], v[122:123], v[226:227] op_sel_hi:[1,0]
	v_cvt_pk_bf16_f32 v152, v124, v125
	v_cvt_pk_bf16_f32 v153, v126, v127
	v_cvt_pk_bf16_f32 v154, v120, v121
	v_cvt_pk_bf16_f32 v155, v122, v123
	global_store_dwordx4 v186, v[152:155], s[0:1]
	v_pk_mul_f32 v[116:117], v[116:117], v[226:227] op_sel_hi:[1,0]
	v_pk_mul_f32 v[118:119], v[118:119], v[226:227] op_sel_hi:[1,0]
	v_pk_mul_f32 v[112:113], v[112:113], v[226:227] op_sel_hi:[1,0]
	v_pk_mul_f32 v[114:115], v[114:115], v[226:227] op_sel_hi:[1,0]
	v_cvt_pk_bf16_f32 v192, v116, v117
	v_cvt_pk_bf16_f32 v193, v118, v119
	v_cvt_pk_bf16_f32 v194, v112, v113
	v_cvt_pk_bf16_f32 v195, v114, v115
	global_store_dwordx4 v186, v[192:195], s[0:1] offset:256
	s_waitcnt vmcnt(14)
	v_pk_add_f32 v[188:189], v[156:157], v[158:159]
	v_pk_add_f32 v[224:225], v[196:197], v[198:199]
	v_add_u32_e32 v186, 0x8000, v185
	v_pk_add_f32 v[188:189], v[188:189], v[224:225]
	s_nop 0
	v_add_f32_e32 v188, v188, v189
	v_fmamk_f32 v188, v188, 0x3b800000, v150
	v_mul_f32_e32 v189, 0x4b800000, v188
	v_cmp_gt_f32_e32 vcc, s75, v188
	s_nop 1
	v_cndmask_b32_e32 v188, v188, v189, vcc
	v_rsq_f32_e32 v226, v188
	s_nop 0
	v_mul_f32_e32 v227, 0x45800000, v226
	v_cndmask_b32_e32 v226, v226, v227, vcc
	v_pk_mul_f32 v[108:109], v[108:109], v[226:227] op_sel_hi:[1,0]
	v_pk_mul_f32 v[110:111], v[110:111], v[226:227] op_sel_hi:[1,0]
	v_pk_mul_f32 v[104:105], v[104:105], v[226:227] op_sel_hi:[1,0]
	v_pk_mul_f32 v[106:107], v[106:107], v[226:227] op_sel_hi:[1,0]
	v_cvt_pk_bf16_f32 v156, v108, v109
	v_cvt_pk_bf16_f32 v157, v110, v111
	v_cvt_pk_bf16_f32 v158, v104, v105
	v_cvt_pk_bf16_f32 v159, v106, v107
	global_store_dwordx4 v186, v[156:159], s[0:1]
	v_pk_mul_f32 v[100:101], v[100:101], v[226:227] op_sel_hi:[1,0]
	v_pk_mul_f32 v[102:103], v[102:103], v[226:227] op_sel_hi:[1,0]
	v_pk_mul_f32 v[96:97], v[96:97], v[226:227] op_sel_hi:[1,0]
	v_pk_mul_f32 v[98:99], v[98:99], v[226:227] op_sel_hi:[1,0]
	v_cvt_pk_bf16_f32 v196, v100, v101
	v_cvt_pk_bf16_f32 v197, v102, v103
	v_cvt_pk_bf16_f32 v198, v96, v97
	v_cvt_pk_bf16_f32 v199, v98, v99
	global_store_dwordx4 v186, v[196:199], s[0:1] offset:256
	s_waitcnt vmcnt(14)
	v_pk_add_f32 v[188:189], v[160:161], v[162:163]
	v_pk_add_f32 v[224:225], v[200:201], v[202:203]
	v_add_u32_e32 v186, 0x10000, v185
	v_pk_add_f32 v[188:189], v[188:189], v[224:225]
	s_nop 0
	v_add_f32_e32 v188, v188, v189
	v_fmamk_f32 v188, v188, 0x3b800000, v150
	v_mul_f32_e32 v189, 0x4b800000, v188
	v_cmp_gt_f32_e32 vcc, s75, v188
	s_nop 1
	v_cndmask_b32_e32 v188, v188, v189, vcc
	v_rsq_f32_e32 v226, v188
	s_nop 0
	v_mul_f32_e32 v227, 0x45800000, v226
	v_cndmask_b32_e32 v226, v226, v227, vcc
	v_pk_mul_f32 v[92:93], v[92:93], v[226:227] op_sel_hi:[1,0]
	v_pk_mul_f32 v[94:95], v[94:95], v[226:227] op_sel_hi:[1,0]
	v_pk_mul_f32 v[88:89], v[88:89], v[226:227] op_sel_hi:[1,0]
	v_pk_mul_f32 v[90:91], v[90:91], v[226:227] op_sel_hi:[1,0]
	v_cvt_pk_bf16_f32 v160, v92, v93
	v_cvt_pk_bf16_f32 v161, v94, v95
	v_cvt_pk_bf16_f32 v162, v88, v89
	v_cvt_pk_bf16_f32 v163, v90, v91
	global_store_dwordx4 v186, v[160:163], s[0:1]
	v_pk_mul_f32 v[84:85], v[84:85], v[226:227] op_sel_hi:[1,0]
	v_pk_mul_f32 v[86:87], v[86:87], v[226:227] op_sel_hi:[1,0]
	v_pk_mul_f32 v[80:81], v[80:81], v[226:227] op_sel_hi:[1,0]
	v_pk_mul_f32 v[82:83], v[82:83], v[226:227] op_sel_hi:[1,0]
	v_cvt_pk_bf16_f32 v200, v84, v85
	v_cvt_pk_bf16_f32 v201, v86, v87
	v_cvt_pk_bf16_f32 v202, v80, v81
	v_cvt_pk_bf16_f32 v203, v82, v83
	global_store_dwordx4 v186, v[200:203], s[0:1] offset:256
	s_waitcnt vmcnt(14)
	v_pk_add_f32 v[188:189], v[164:165], v[166:167]
	v_pk_add_f32 v[224:225], v[204:205], v[206:207]
	v_add_u32_e32 v186, 0x18000, v185
	v_pk_add_f32 v[188:189], v[188:189], v[224:225]
	s_nop 0
	v_add_f32_e32 v188, v188, v189
	v_fmamk_f32 v188, v188, 0x3b800000, v150
	v_mul_f32_e32 v189, 0x4b800000, v188
	v_cmp_gt_f32_e32 vcc, s75, v188
	s_nop 1
	v_cndmask_b32_e32 v188, v188, v189, vcc
	v_rsq_f32_e32 v226, v188
	s_nop 0
	v_mul_f32_e32 v227, 0x45800000, v226
	v_cndmask_b32_e32 v226, v226, v227, vcc
	v_pk_mul_f32 v[76:77], v[76:77], v[226:227] op_sel_hi:[1,0]
	v_pk_mul_f32 v[78:79], v[78:79], v[226:227] op_sel_hi:[1,0]
	v_pk_mul_f32 v[72:73], v[72:73], v[226:227] op_sel_hi:[1,0]
	v_pk_mul_f32 v[74:75], v[74:75], v[226:227] op_sel_hi:[1,0]
	v_cvt_pk_bf16_f32 v164, v76, v77
	v_cvt_pk_bf16_f32 v165, v78, v79
	v_cvt_pk_bf16_f32 v166, v72, v73
	v_cvt_pk_bf16_f32 v167, v74, v75
	global_store_dwordx4 v186, v[164:167], s[0:1]
	v_pk_mul_f32 v[68:69], v[68:69], v[226:227] op_sel_hi:[1,0]
	v_pk_mul_f32 v[70:71], v[70:71], v[226:227] op_sel_hi:[1,0]
	v_pk_mul_f32 v[64:65], v[64:65], v[226:227] op_sel_hi:[1,0]
	v_pk_mul_f32 v[66:67], v[66:67], v[226:227] op_sel_hi:[1,0]
	v_cvt_pk_bf16_f32 v204, v68, v69
	v_cvt_pk_bf16_f32 v205, v70, v71
	v_cvt_pk_bf16_f32 v206, v64, v65
	v_cvt_pk_bf16_f32 v207, v66, v67
	global_store_dwordx4 v186, v[204:207], s[0:1] offset:256
	s_waitcnt vmcnt(14)
	v_pk_add_f32 v[188:189], v[168:169], v[170:171]
	v_pk_add_f32 v[224:225], v[208:209], v[210:211]
	v_add_u32_e32 v186, 0x40000, v185
	v_pk_add_f32 v[188:189], v[188:189], v[224:225]
	s_nop 0
	v_add_f32_e32 v188, v188, v189
	v_fmamk_f32 v188, v188, 0x3b800000, v150
	v_mul_f32_e32 v189, 0x4b800000, v188
	v_cmp_gt_f32_e32 vcc, s75, v188
	s_nop 1
	v_cndmask_b32_e32 v188, v188, v189, vcc
	v_rsq_f32_e32 v226, v188
	s_nop 0
	v_mul_f32_e32 v227, 0x45800000, v226
	v_cndmask_b32_e32 v226, v226, v227, vcc
	v_pk_mul_f32 v[60:61], v[60:61], v[226:227] op_sel_hi:[1,0]
	v_pk_mul_f32 v[62:63], v[62:63], v[226:227] op_sel_hi:[1,0]
	v_pk_mul_f32 v[56:57], v[56:57], v[226:227] op_sel_hi:[1,0]
	v_pk_mul_f32 v[58:59], v[58:59], v[226:227] op_sel_hi:[1,0]
	v_cvt_pk_bf16_f32 v168, v60, v61
	v_cvt_pk_bf16_f32 v169, v62, v63
	v_cvt_pk_bf16_f32 v170, v56, v57
	v_cvt_pk_bf16_f32 v171, v58, v59
	global_store_dwordx4 v186, v[168:171], s[0:1]
	v_pk_mul_f32 v[52:53], v[52:53], v[226:227] op_sel_hi:[1,0]
	v_pk_mul_f32 v[54:55], v[54:55], v[226:227] op_sel_hi:[1,0]
	v_pk_mul_f32 v[48:49], v[48:49], v[226:227] op_sel_hi:[1,0]
	v_pk_mul_f32 v[50:51], v[50:51], v[226:227] op_sel_hi:[1,0]
	v_cvt_pk_bf16_f32 v208, v52, v53
	v_cvt_pk_bf16_f32 v209, v54, v55
	v_cvt_pk_bf16_f32 v210, v48, v49
	v_cvt_pk_bf16_f32 v211, v50, v51
	global_store_dwordx4 v186, v[208:211], s[0:1] offset:256
	s_waitcnt vmcnt(14)
	v_pk_add_f32 v[188:189], v[172:173], v[174:175]
	v_pk_add_f32 v[224:225], v[212:213], v[214:215]
	v_add_u32_e32 v186, 0x48000, v185
	v_pk_add_f32 v[188:189], v[188:189], v[224:225]
	s_nop 0
	v_add_f32_e32 v188, v188, v189
	v_fmamk_f32 v188, v188, 0x3b800000, v150
	v_mul_f32_e32 v189, 0x4b800000, v188
	v_cmp_gt_f32_e32 vcc, s75, v188
	s_nop 1
	v_cndmask_b32_e32 v188, v188, v189, vcc
	v_rsq_f32_e32 v226, v188
	s_nop 0
	v_mul_f32_e32 v227, 0x45800000, v226
	v_cndmask_b32_e32 v226, v226, v227, vcc
	v_pk_mul_f32 v[44:45], v[44:45], v[226:227] op_sel_hi:[1,0]
	v_pk_mul_f32 v[46:47], v[46:47], v[226:227] op_sel_hi:[1,0]
	v_pk_mul_f32 v[40:41], v[40:41], v[226:227] op_sel_hi:[1,0]
	v_pk_mul_f32 v[42:43], v[42:43], v[226:227] op_sel_hi:[1,0]
	v_cvt_pk_bf16_f32 v172, v44, v45
	v_cvt_pk_bf16_f32 v173, v46, v47
	v_cvt_pk_bf16_f32 v174, v40, v41
	v_cvt_pk_bf16_f32 v175, v42, v43
	global_store_dwordx4 v186, v[172:175], s[0:1]
	v_pk_mul_f32 v[36:37], v[36:37], v[226:227] op_sel_hi:[1,0]
	v_pk_mul_f32 v[38:39], v[38:39], v[226:227] op_sel_hi:[1,0]
	v_pk_mul_f32 v[32:33], v[32:33], v[226:227] op_sel_hi:[1,0]
	v_pk_mul_f32 v[34:35], v[34:35], v[226:227] op_sel_hi:[1,0]
	v_cvt_pk_bf16_f32 v212, v36, v37
	v_cvt_pk_bf16_f32 v213, v38, v39
	v_cvt_pk_bf16_f32 v214, v32, v33
	v_cvt_pk_bf16_f32 v215, v34, v35
	global_store_dwordx4 v186, v[212:215], s[0:1] offset:256
	s_waitcnt vmcnt(14)
	v_pk_add_f32 v[188:189], v[176:177], v[178:179]
	v_pk_add_f32 v[224:225], v[216:217], v[218:219]
	v_add_u32_e32 v186, 0x50000, v185
	v_pk_add_f32 v[188:189], v[188:189], v[224:225]
	s_nop 0
	v_add_f32_e32 v188, v188, v189
	v_fmamk_f32 v188, v188, 0x3b800000, v150
	v_mul_f32_e32 v189, 0x4b800000, v188
	v_cmp_gt_f32_e32 vcc, s75, v188
	s_nop 1
	v_cndmask_b32_e32 v188, v188, v189, vcc
	v_rsq_f32_e32 v226, v188
	s_nop 0
	v_mul_f32_e32 v227, 0x45800000, v226
	v_cndmask_b32_e32 v226, v226, v227, vcc
	v_pk_mul_f32 v[28:29], v[28:29], v[226:227] op_sel_hi:[1,0]
	v_pk_mul_f32 v[30:31], v[30:31], v[226:227] op_sel_hi:[1,0]
	v_pk_mul_f32 v[24:25], v[24:25], v[226:227] op_sel_hi:[1,0]
	v_pk_mul_f32 v[26:27], v[26:27], v[226:227] op_sel_hi:[1,0]
	v_cvt_pk_bf16_f32 v176, v28, v29
	v_cvt_pk_bf16_f32 v177, v30, v31
	v_cvt_pk_bf16_f32 v178, v24, v25
	v_cvt_pk_bf16_f32 v179, v26, v27
	global_store_dwordx4 v186, v[176:179], s[0:1]
	v_pk_mul_f32 v[20:21], v[20:21], v[226:227] op_sel_hi:[1,0]
	v_pk_mul_f32 v[22:23], v[22:23], v[226:227] op_sel_hi:[1,0]
	v_pk_mul_f32 v[16:17], v[16:17], v[226:227] op_sel_hi:[1,0]
	v_pk_mul_f32 v[18:19], v[18:19], v[226:227] op_sel_hi:[1,0]
	v_cvt_pk_bf16_f32 v216, v20, v21
	v_cvt_pk_bf16_f32 v217, v22, v23
	v_cvt_pk_bf16_f32 v218, v16, v17
	v_cvt_pk_bf16_f32 v219, v18, v19
	global_store_dwordx4 v186, v[216:219], s[0:1] offset:256
	s_waitcnt vmcnt(14)
	v_pk_add_f32 v[188:189], v[180:181], v[182:183]
	v_pk_add_f32 v[224:225], v[220:221], v[222:223]
	v_add_u32_e32 v186, 0x58000, v185
	v_pk_add_f32 v[188:189], v[188:189], v[224:225]
	s_nop 0
	v_add_f32_e32 v188, v188, v189
	v_fmamk_f32 v188, v188, 0x3b800000, v150
	v_mul_f32_e32 v189, 0x4b800000, v188
	v_cmp_gt_f32_e32 vcc, s75, v188
	s_nop 1
	v_cndmask_b32_e32 v188, v188, v189, vcc
	v_rsq_f32_e32 v226, v188
	s_nop 0
	v_mul_f32_e32 v227, 0x45800000, v226
	v_cndmask_b32_e32 v226, v226, v227, vcc
	v_pk_mul_f32 v[12:13], v[12:13], v[226:227] op_sel_hi:[1,0]
	v_pk_mul_f32 v[14:15], v[14:15], v[226:227] op_sel_hi:[1,0]
	v_pk_mul_f32 v[8:9], v[8:9], v[226:227] op_sel_hi:[1,0]
	v_pk_mul_f32 v[10:11], v[10:11], v[226:227] op_sel_hi:[1,0]
	v_cvt_pk_bf16_f32 v180, v12, v13
	v_cvt_pk_bf16_f32 v181, v14, v15
	v_cvt_pk_bf16_f32 v182, v8, v9
	v_cvt_pk_bf16_f32 v183, v10, v11
	global_store_dwordx4 v186, v[180:183], s[0:1]
	v_pk_mul_f32 v[4:5], v[4:5], v[226:227] op_sel_hi:[1,0]
	v_pk_mul_f32 v[6:7], v[6:7], v[226:227] op_sel_hi:[1,0]
	v_pk_mul_f32 v[0:1], v[0:1], v[226:227] op_sel_hi:[1,0]
	v_pk_mul_f32 v[2:3], v[2:3], v[226:227] op_sel_hi:[1,0]
	v_cvt_pk_bf16_f32 v220, v4, v5
	v_cvt_pk_bf16_f32 v221, v6, v7
	v_cvt_pk_bf16_f32 v222, v0, v1
	v_cvt_pk_bf16_f32 v223, v2, v3
	global_store_dwordx4 v186, v[220:223], s[0:1] offset:256
	s_and_b64 vcc, exec, s[4:5]
	s_mov_b64 s[0:1], -1
	s_cbranch_vccnz .LBB0_442
	s_andn2_b64 vcc, exec, s[38:39]
	s_cbranch_vccnz .LBB0_441
	s_barrier
	s_branch .LBB0_441

.LBB0_1036:
	v_mov_b32_e32 v130, v191
	s_waitcnt vmcnt(0)
	s_barrier
	v_lshl_or_b32 v216, s0, 7, v142
	v_lshlrev_b32_e32 v216, 2, v216
	v_add_u32_e32 v217, 0x2c00, v216
	global_load_dwordx4 v[148:151], v216, s[16:17]
	global_load_dwordx4 v[152:155], v216, s[16:17] offset:16
	global_load_dwordx4 v[180:183], v217, s[16:17]
	global_load_dwordx4 v[184:187], v217, s[16:17] offset:16
	global_load_dwordx4 v[156:159], v216, s[8:9]
	global_load_dwordx4 v[160:163], v216, s[8:9] offset:16
	global_load_dwordx4 v[192:195], v217, s[8:9]
	global_load_dwordx4 v[196:199], v217, s[8:9] offset:16
	global_load_dwordx4 v[164:167], v216, s[20:21]
	global_load_dwordx4 v[168:171], v216, s[20:21] offset:16
	global_load_dwordx4 v[200:203], v217, s[20:21]
	global_load_dwordx4 v[204:207], v217, s[20:21] offset:16
	global_load_dwordx4 v[172:175], v216, s[18:19]
	global_load_dwordx4 v[176:179], v216, s[18:19] offset:16
	global_load_dwordx4 v[208:211], v217, s[18:19]
	global_load_dwordx4 v[212:215], v217, s[18:19] offset:16
	s_lshl_b32 s1, s1, 6
	v_and_or_b32 v132, v130, 15, s61
	v_and_b32_e32 v130, 48, v130
	s_add_i32 s1, s1, 0
	v_mul_lo_u32 v132, v132, s50
	v_add3_u32 v130, s1, v130, v132
	v_cvt_pk_bf16_f32 v68, v68, v69
	v_cvt_pk_bf16_f32 v69, v70, v71
	v_cvt_pk_bf16_f32 v70, v64, v65
	v_add_u32_e32 v64, 0x10800, v130
	v_cvt_pk_bf16_f32 v60, v60, v61
	v_cvt_pk_bf16_f32 v61, v62, v63
	v_cvt_pk_bf16_f32 v62, v56, v57
	v_cvt_pk_bf16_f32 v63, v58, v59
	ds_write_b128 v64, v[60:63]
	v_cvt_pk_bf16_f32 v52, v52, v53
	v_cvt_pk_bf16_f32 v53, v54, v55
	v_cvt_pk_bf16_f32 v54, v48, v49
	v_cvt_pk_bf16_f32 v55, v50, v51
	v_add_u32_e32 v48, 0x10900, v130
	v_cvt_pk_bf16_f32 v36, v36, v37
	v_cvt_pk_bf16_f32 v37, v38, v39
	v_cvt_pk_bf16_f32 v38, v32, v33
	v_cvt_pk_bf16_f32 v39, v34, v35
	v_add_u32_e32 v32, 0x12a00, v130
	v_cvt_pk_bf16_f32 v20, v20, v21
	v_cvt_pk_bf16_f32 v21, v22, v23
	v_cvt_pk_bf16_f32 v22, v16, v17
	v_cvt_pk_bf16_f32 v23, v18, v19
	v_add_u32_e32 v16, 0x14b00, v130
	v_lshl_or_b32 v64, s0, 7, v142
	v_cvt_pk_bf16_f32 v124, v124, v125
	v_cvt_pk_bf16_f32 v125, v126, v127
	v_cvt_pk_bf16_f32 v126, v120, v121
	v_cvt_pk_bf16_f32 v127, v122, v123
	v_cvt_pk_bf16_f32 v116, v116, v117
	v_cvt_pk_bf16_f32 v117, v118, v119
	v_cvt_pk_bf16_f32 v118, v112, v113
	v_cvt_pk_bf16_f32 v119, v114, v115
	v_cvt_pk_bf16_f32 v108, v108, v109
	v_cvt_pk_bf16_f32 v109, v110, v111
	v_cvt_pk_bf16_f32 v110, v104, v105
	v_cvt_pk_bf16_f32 v111, v106, v107
	v_cvt_pk_bf16_f32 v100, v100, v101
	v_cvt_pk_bf16_f32 v101, v102, v103
	v_cvt_pk_bf16_f32 v102, v96, v97
	v_cvt_pk_bf16_f32 v103, v98, v99
	v_cvt_pk_bf16_f32 v92, v92, v93
	v_cvt_pk_bf16_f32 v93, v94, v95
	v_cvt_pk_bf16_f32 v94, v88, v89
	v_cvt_pk_bf16_f32 v95, v90, v91
	v_cvt_pk_bf16_f32 v84, v84, v85
	v_cvt_pk_bf16_f32 v85, v86, v87
	v_cvt_pk_bf16_f32 v86, v80, v81
	v_cvt_pk_bf16_f32 v87, v82, v83
	v_cvt_pk_bf16_f32 v76, v76, v77
	v_cvt_pk_bf16_f32 v77, v78, v79
	v_cvt_pk_bf16_f32 v78, v72, v73
	v_cvt_pk_bf16_f32 v79, v74, v75
	v_cvt_pk_bf16_f32 v71, v66, v67
	ds_write_b128 v48, v[52:55]
	v_add_u32_e32 v48, 0x12900, v130
	v_cvt_pk_bf16_f32 v44, v44, v45
	v_cvt_pk_bf16_f32 v45, v46, v47
	v_cvt_pk_bf16_f32 v46, v40, v41
	v_cvt_pk_bf16_f32 v47, v42, v43
	ds_write_b128 v32, v[36:39]
	v_add_u32_e32 v32, 0x14a00, v130
	v_cvt_pk_bf16_f32 v28, v28, v29
	v_cvt_pk_bf16_f32 v29, v30, v31
	v_cvt_pk_bf16_f32 v30, v24, v25
	v_cvt_pk_bf16_f32 v31, v26, v27
	ds_write_b128 v16, v[20:23]
	v_add_u32_e32 v16, 0x16b00, v130
	v_cvt_pk_bf16_f32 v12, v12, v13
	v_cvt_pk_bf16_f32 v13, v14, v15
	v_cvt_pk_bf16_f32 v14, v8, v9
	v_cvt_pk_bf16_f32 v15, v10, v11
	v_cvt_pk_bf16_f32 v4, v4, v5
	v_cvt_pk_bf16_f32 v5, v6, v7
	v_cvt_pk_bf16_f32 v6, v0, v1
	v_cvt_pk_bf16_f32 v7, v2, v3
	v_add_u32_e32 v0, 0x16c00, v130
	v_ashrrev_i32_e32 v65, 31, v64
	ds_write_b128 v130, v[124:127]
	ds_write_b128 v130, v[116:119] offset:256
	ds_write_b128 v130, v[108:111] offset:8448
	ds_write_b128 v130, v[100:103] offset:8704
	ds_write_b128 v130, v[92:95] offset:16896
	ds_write_b128 v130, v[84:87] offset:17152
	ds_write_b128 v130, v[76:79] offset:25344
	ds_write_b128 v130, v[68:71] offset:25600
	ds_write_b128 v48, v[44:47]
	ds_write_b128 v32, v[28:31]
	ds_write_b128 v16, v[12:15]
	ds_write_b128 v0, v[4:7]
	s_waitcnt lgkmcnt(0)
	s_barrier
	s_mulk_i32 s57, 0xfe
	s_mulk_i32 s59, 0xfe
	s_sub_i32 s0, s57, s59
	s_mul_i32 s58, s58, 0xa6b0
	s_sub_i32 s10, s0, s58
	v_lshl_add_u64 v[64:65], v[64:65], 1, s[14:15]
	s_add_i32 s10, s10, -2
	s_movk_i32 s11, 0xfbe0
	v_lshlrev_b32_e32 v66, 1, v143
	v_mul_u32_u24_e32 v223, 0x210, v143
	v_add_u32_e32 v223, v223, v144
	v_mov_b32_e32 v218, 0xbdd2d3e7
	v_mov_b32_e32 v219, 0xbdd2d3e7
	v_mov_b32_e32 v220, 0xc0135761
	v_mov_b32_e32 v221, 0xc0135761
	s_waitcnt vmcnt(0)
	s_branch .LBB0_1038
.LBB0_1037:
	s_or_b64 exec, exec, s[0:1]
	s_add_i32 s11, s11, 0x8400
	s_cmp_lg_u32 s11, 0x20be0
	v_add_u32_e32 v66, 64, v66
	s_cbranch_scc0 .LBB0_1022
.LBB0_1038:
	v_add_u32_e32 v67, s10, v66
	v_cmp_lt_u32_e32 vcc, 1, v66
	v_cmp_gt_i32_e64 s[0:1], s54, v67
	s_and_b64 s[4:5], vcc, s[0:1]
	s_and_saveexec_b64 s[0:1], s[4:5]
	s_cbranch_execz .LBB0_1037
	v_add_u32_e32 v222, s11, v223
	ds_read_b128 v[68:71], v222
	ds_read_b128 v[72:75], v222 offset:528
	ds_read_b128 v[76:79], v222 offset:1056
	ds_read_b128 v[80:83], v222 offset:1584
	ds_read_b128 v[84:87], v222 offset:256
	ds_read_b128 v[88:91], v222 offset:784
	ds_read_b128 v[92:95], v222 offset:1312
	ds_read_b128 v[96:99], v222 offset:1840
	s_waitcnt lgkmcnt(4)
	v_lshlrev_b32_e32 v0, 16, v68
	v_and_b32_e32 v1, 0xffff0000, v68
	v_lshlrev_b32_e32 v2, 16, v69
	v_and_b32_e32 v3, 0xffff0000, v69
	v_lshlrev_b32_e32 v4, 16, v70
	v_and_b32_e32 v5, 0xffff0000, v70
	v_lshlrev_b32_e32 v6, 16, v71
	v_and_b32_e32 v7, 0xffff0000, v71
	v_lshlrev_b32_e32 v8, 16, v72
	v_and_b32_e32 v9, 0xffff0000, v72
	v_lshlrev_b32_e32 v10, 16, v73
	v_and_b32_e32 v11, 0xffff0000, v73
	v_lshlrev_b32_e32 v12, 16, v74
	v_and_b32_e32 v13, 0xffff0000, v74
	v_lshlrev_b32_e32 v14, 16, v75
	v_and_b32_e32 v15, 0xffff0000, v75
	v_lshlrev_b32_e32 v16, 16, v76
	v_and_b32_e32 v17, 0xffff0000, v76
	v_lshlrev_b32_e32 v18, 16, v77
	v_and_b32_e32 v19, 0xffff0000, v77
	v_lshlrev_b32_e32 v20, 16, v78
	v_and_b32_e32 v21, 0xffff0000, v78
	v_lshlrev_b32_e32 v22, 16, v79
	v_and_b32_e32 v23, 0xffff0000, v79
	v_lshlrev_b32_e32 v24, 16, v80
	v_and_b32_e32 v25, 0xffff0000, v80
	v_lshlrev_b32_e32 v26, 16, v81
	v_and_b32_e32 v27, 0xffff0000, v81
	v_lshlrev_b32_e32 v28, 16, v82
	v_and_b32_e32 v29, 0xffff0000, v82
	v_lshlrev_b32_e32 v30, 16, v83
	v_and_b32_e32 v31, 0xffff0000, v83
	s_waitcnt lgkmcnt(0)
	v_lshlrev_b32_e32 v32, 16, v84
	v_and_b32_e32 v33, 0xffff0000, v84
	v_lshlrev_b32_e32 v34, 16, v85
	v_and_b32_e32 v35, 0xffff0000, v85
	v_lshlrev_b32_e32 v36, 16, v86
	v_and_b32_e32 v37, 0xffff0000, v86
	v_lshlrev_b32_e32 v38, 16, v87
	v_and_b32_e32 v39, 0xffff0000, v87
	v_lshlrev_b32_e32 v40, 16, v88
	v_and_b32_e32 v41, 0xffff0000, v88
	v_lshlrev_b32_e32 v42, 16, v89
	v_and_b32_e32 v43, 0xffff0000, v89
	v_lshlrev_b32_e32 v44, 16, v90
	v_and_b32_e32 v45, 0xffff0000, v90
	v_lshlrev_b32_e32 v46, 16, v91
	v_and_b32_e32 v47, 0xffff0000, v91
	v_lshlrev_b32_e32 v48, 16, v92
	v_and_b32_e32 v49, 0xffff0000, v92
	v_lshlrev_b32_e32 v50, 16, v93
	v_and_b32_e32 v51, 0xffff0000, v93
	v_lshlrev_b32_e32 v52, 16, v94
	v_and_b32_e32 v53, 0xffff0000, v94
	v_lshlrev_b32_e32 v54, 16, v95
	v_and_b32_e32 v55, 0xffff0000, v95
	v_lshlrev_b32_e32 v56, 16, v96
	v_and_b32_e32 v57, 0xffff0000, v96
	v_lshlrev_b32_e32 v58, 16, v97
	v_and_b32_e32 v59, 0xffff0000, v97
	v_lshlrev_b32_e32 v60, 16, v98
	v_and_b32_e32 v61, 0xffff0000, v98
	v_lshlrev_b32_e32 v62, 16, v99
	v_and_b32_e32 v63, 0xffff0000, v99
	v_and_b32_e32 v222, 0xfff, v67
	v_cmp_eq_u32_e32 vcc, 0, v222
	s_cbranch_vccz .Lconv2_common
	v_cmp_ne_u32_e32 vcc, 0, v222
	s_nop 1
	v_cndmask_b32_e32 v0, 0, v0, vcc
	v_cndmask_b32_e32 v1, 0, v1, vcc
	v_cndmask_b32_e32 v2, 0, v2, vcc
	v_cndmask_b32_e32 v3, 0, v3, vcc
	v_cndmask_b32_e32 v4, 0, v4, vcc
	v_cndmask_b32_e32 v5, 0, v5, vcc
	v_cndmask_b32_e32 v6, 0, v6, vcc
	v_cndmask_b32_e32 v7, 0, v7, vcc
	v_cndmask_b32_e32 v8, 0, v8, vcc
	v_cndmask_b32_e32 v9, 0, v9, vcc
	v_cndmask_b32_e32 v10, 0, v10, vcc
	v_cndmask_b32_e32 v11, 0, v11, vcc
	v_cndmask_b32_e32 v12, 0, v12, vcc
	v_cndmask_b32_e32 v13, 0, v13, vcc
	v_cndmask_b32_e32 v14, 0, v14, vcc
	v_cndmask_b32_e32 v15, 0, v15, vcc
	v_cndmask_b32_e32 v32, 0, v32, vcc
	v_cndmask_b32_e32 v33, 0, v33, vcc
	v_cndmask_b32_e32 v34, 0, v34, vcc
	v_cndmask_b32_e32 v35, 0, v35, vcc
	v_cndmask_b32_e32 v36, 0, v36, vcc
	v_cndmask_b32_e32 v37, 0, v37, vcc
	v_cndmask_b32_e32 v38, 0, v38, vcc
	v_cndmask_b32_e32 v39, 0, v39, vcc
	v_cndmask_b32_e32 v40, 0, v40, vcc
	v_cndmask_b32_e32 v41, 0, v41, vcc
	v_cndmask_b32_e32 v42, 0, v42, vcc
	v_cndmask_b32_e32 v43, 0, v43, vcc
	v_cndmask_b32_e32 v44, 0, v44, vcc
	v_cndmask_b32_e32 v45, 0, v45, vcc
	v_cndmask_b32_e32 v46, 0, v46, vcc
	v_cndmask_b32_e32 v47, 0, v47, vcc
.Lconv2_common:
	v_pk_fma_f32 v[68:69], v[164:165], v[16:17], v[172:173]
	v_pk_fma_f32 v[70:71], v[166:167], v[18:19], v[174:175]
	v_pk_fma_f32 v[72:73], v[168:169], v[20:21], v[176:177]
	v_pk_fma_f32 v[74:75], v[170:171], v[22:23], v[178:179]
	v_pk_fma_f32 v[68:69], v[156:157], v[8:9], v[68:69]
	v_pk_fma_f32 v[70:71], v[158:159], v[10:11], v[70:71]
	v_pk_fma_f32 v[72:73], v[160:161], v[12:13], v[72:73]
	v_pk_fma_f32 v[74:75], v[162:163], v[14:15], v[74:75]
	v_pk_fma_f32 v[68:69], v[148:149], v[0:1], v[68:69]
	v_pk_fma_f32 v[70:71], v[150:151], v[2:3], v[70:71]
	v_pk_fma_f32 v[72:73], v[152:153], v[4:5], v[72:73]
	v_pk_fma_f32 v[74:75], v[154:155], v[6:7], v[74:75]
	v_pk_fma_f32 v[76:77], v[164:165], v[24:25], v[172:173]
	v_pk_fma_f32 v[78:79], v[166:167], v[26:27], v[174:175]
	v_pk_fma_f32 v[80:81], v[168:169], v[28:29], v[176:177]
	v_pk_fma_f32 v[82:83], v[170:171], v[30:31], v[178:179]
	v_pk_fma_f32 v[76:77], v[156:157], v[16:17], v[76:77]
	v_pk_fma_f32 v[78:79], v[158:159], v[18:19], v[78:79]
	v_pk_fma_f32 v[80:81], v[160:161], v[20:21], v[80:81]
	v_pk_fma_f32 v[82:83], v[162:163], v[22:23], v[82:83]
	v_pk_fma_f32 v[76:77], v[148:149], v[8:9], v[76:77]
	v_pk_fma_f32 v[78:79], v[150:151], v[10:11], v[78:79]
	v_pk_fma_f32 v[80:81], v[152:153], v[12:13], v[80:81]
	v_pk_fma_f32 v[82:83], v[154:155], v[14:15], v[82:83]
	v_pk_mul_f32 v[100:101], v[68:69], v[68:69]
	v_pk_mul_f32 v[102:103], v[70:71], v[70:71]
	v_pk_mul_f32 v[104:105], v[72:73], v[72:73]
	v_pk_mul_f32 v[106:107], v[74:75], v[74:75]
	v_pk_mul_f32 v[108:109], v[76:77], v[76:77]
	v_pk_mul_f32 v[110:111], v[78:79], v[78:79]
	v_pk_mul_f32 v[112:113], v[80:81], v[80:81]
	v_pk_mul_f32 v[114:115], v[82:83], v[82:83]
	v_pk_fma_f32 v[100:101], v[100:101], v[218:219], v[220:221]
	v_pk_fma_f32 v[102:103], v[102:103], v[218:219], v[220:221]
	v_pk_fma_f32 v[104:105], v[104:105], v[218:219], v[220:221]
	v_pk_fma_f32 v[106:107], v[106:107], v[218:219], v[220:221]
	v_pk_fma_f32 v[108:109], v[108:109], v[218:219], v[220:221]
	v_pk_fma_f32 v[110:111], v[110:111], v[218:219], v[220:221]
	v_pk_fma_f32 v[112:113], v[112:113], v[218:219], v[220:221]
	v_pk_fma_f32 v[114:115], v[114:115], v[218:219], v[220:221]
	v_pk_mul_f32 v[100:101], v[68:69], v[100:101]
	v_pk_mul_f32 v[102:103], v[70:71], v[102:103]
	v_pk_mul_f32 v[104:105], v[72:73], v[104:105]
	v_pk_mul_f32 v[106:107], v[74:75], v[106:107]
	v_pk_mul_f32 v[108:109], v[76:77], v[108:109]
	v_pk_mul_f32 v[110:111], v[78:79], v[110:111]
	v_pk_mul_f32 v[112:113], v[80:81], v[112:113]
	v_pk_mul_f32 v[114:115], v[82:83], v[114:115]
	v_exp_f32_e32 v100, v100
	v_exp_f32_e32 v101, v101
	v_exp_f32_e32 v102, v102
	v_exp_f32_e32 v103, v103
	v_exp_f32_e32 v104, v104
	v_exp_f32_e32 v105, v105
	v_exp_f32_e32 v106, v106
	v_exp_f32_e32 v107, v107
	v_exp_f32_e32 v108, v108
	v_exp_f32_e32 v109, v109
	v_exp_f32_e32 v110, v110
	v_exp_f32_e32 v111, v111
	v_exp_f32_e32 v112, v112
	v_exp_f32_e32 v113, v113
	v_exp_f32_e32 v114, v114
	v_exp_f32_e32 v115, v115
	v_pk_fma_f32 v[84:85], v[200:201], v[48:49], v[208:209]
	v_pk_fma_f32 v[86:87], v[202:203], v[50:51], v[210:211]
	v_pk_fma_f32 v[88:89], v[204:205], v[52:53], v[212:213]
	v_pk_fma_f32 v[90:91], v[206:207], v[54:55], v[214:215]
	v_pk_fma_f32 v[84:85], v[192:193], v[40:41], v[84:85]
	v_pk_fma_f32 v[86:87], v[194:195], v[42:43], v[86:87]
	v_pk_fma_f32 v[88:89], v[196:197], v[44:45], v[88:89]
	v_pk_fma_f32 v[90:91], v[198:199], v[46:47], v[90:91]
	v_pk_fma_f32 v[84:85], v[180:181], v[32:33], v[84:85]
	v_pk_fma_f32 v[86:87], v[182:183], v[34:35], v[86:87]
	v_pk_fma_f32 v[88:89], v[184:185], v[36:37], v[88:89]
	v_pk_fma_f32 v[90:91], v[186:187], v[38:39], v[90:91]
	v_pk_fma_f32 v[92:93], v[200:201], v[56:57], v[208:209]
	v_pk_fma_f32 v[94:95], v[202:203], v[58:59], v[210:211]
	v_pk_fma_f32 v[96:97], v[204:205], v[60:61], v[212:213]
	v_pk_fma_f32 v[98:99], v[206:207], v[62:63], v[214:215]
	v_pk_fma_f32 v[92:93], v[192:193], v[48:49], v[92:93]
	v_pk_fma_f32 v[94:95], v[194:195], v[50:51], v[94:95]
	v_pk_fma_f32 v[96:97], v[196:197], v[52:53], v[96:97]
	v_pk_fma_f32 v[98:99], v[198:199], v[54:55], v[98:99]
	v_pk_fma_f32 v[92:93], v[180:181], v[40:41], v[92:93]
	v_pk_fma_f32 v[94:95], v[182:183], v[42:43], v[94:95]
	v_pk_fma_f32 v[96:97], v[184:185], v[44:45], v[96:97]
	v_pk_fma_f32 v[98:99], v[186:187], v[46:47], v[98:99]
	v_pk_add_f32 v[100:101], v[100:101], 1.0 op_sel_hi:[1,0]
	v_pk_add_f32 v[102:103], v[102:103], 1.0 op_sel_hi:[1,0]
	v_pk_add_f32 v[104:105], v[104:105], 1.0 op_sel_hi:[1,0]
	v_pk_add_f32 v[106:107], v[106:107], 1.0 op_sel_hi:[1,0]
	v_pk_add_f32 v[108:109], v[108:109], 1.0 op_sel_hi:[1,0]
	v_pk_add_f32 v[110:111], v[110:111], 1.0 op_sel_hi:[1,0]
	v_pk_add_f32 v[112:113], v[112:113], 1.0 op_sel_hi:[1,0]
	v_pk_add_f32 v[114:115], v[114:115], 1.0 op_sel_hi:[1,0]
	v_rcp_f32_e32 v100, v100
	v_rcp_f32_e32 v101, v101
	v_rcp_f32_e32 v102, v102
	v_rcp_f32_e32 v103, v103
	v_rcp_f32_e32 v104, v104
	v_rcp_f32_e32 v105, v105
	v_rcp_f32_e32 v106, v106
	v_rcp_f32_e32 v107, v107
	v_rcp_f32_e32 v108, v108
	v_rcp_f32_e32 v109, v109
	v_rcp_f32_e32 v110, v110
	v_rcp_f32_e32 v111, v111
	v_rcp_f32_e32 v112, v112
	v_rcp_f32_e32 v113, v113
	v_rcp_f32_e32 v114, v114
	v_rcp_f32_e32 v115, v115
	v_add_u32_e32 v222, 1, v67
	v_mad_i64_i32 v[124:125], s[4:5], v67, s56, v[64:65]
	v_mad_i64_i32 v[126:127], s[4:5], v222, s56, v[64:65]
	v_pk_mul_f32 v[68:69], v[68:69], v[100:101]
	v_pk_mul_f32 v[70:71], v[70:71], v[102:103]
	v_pk_mul_f32 v[72:73], v[72:73], v[104:105]
	v_pk_mul_f32 v[74:75], v[74:75], v[106:107]
	v_pk_mul_f32 v[76:77], v[76:77], v[108:109]
	v_pk_mul_f32 v[78:79], v[78:79], v[110:111]
	v_pk_mul_f32 v[80:81], v[80:81], v[112:113]
	v_pk_mul_f32 v[82:83], v[82:83], v[114:115]
	v_pk_mul_f32 v[68:69], v[68:69], v[84:85]
	v_pk_mul_f32 v[70:71], v[70:71], v[86:87]
	v_pk_mul_f32 v[72:73], v[72:73], v[88:89]
	v_pk_mul_f32 v[74:75], v[74:75], v[90:91]
	v_pk_mul_f32 v[76:77], v[76:77], v[92:93]
	v_pk_mul_f32 v[78:79], v[78:79], v[94:95]
	v_pk_mul_f32 v[80:81], v[80:81], v[96:97]
	v_pk_mul_f32 v[82:83], v[82:83], v[98:99]
	v_cvt_pk_bf16_f32 v116, v68, v69
	v_cvt_pk_bf16_f32 v117, v70, v71
	v_cvt_pk_bf16_f32 v118, v72, v73
	v_cvt_pk_bf16_f32 v119, v74, v75
	v_cvt_pk_bf16_f32 v120, v76, v77
	v_cvt_pk_bf16_f32 v121, v78, v79
	v_cvt_pk_bf16_f32 v122, v80, v81
	v_cvt_pk_bf16_f32 v123, v82, v83
	global_store_dwordx4 v[124:125], v[116:119], off
	global_store_dwordx4 v[126:127], v[120:123], off
	s_branch .LBB0_1037
